# Q up-projection epilogue (non-rotary tiles): per-row scales requested before the K loop, eight serialized load+drain steps removed
# baseline (speedup 1.0000x reference)
; template <class Epi, class Sched, bool ALIGN_EPI = false, bool SP2 = false>
; __device__ __forceinline__ void gemm_phase(LAS unsigned char* lds, const Gemm g, const Sched S, const Epi E) {
;     ...
; #pragma unroll
;         for (int a = 0; a < 2; ++a)
; #pragma unroll
;             for (int b = 0; b < 2; ++b)
; #pragma unroll
;                 for (int m = 0; m < 4; ++m)
; #pragma unroll
;                     for (int n = 0; n < 2; ++n) acc[a][b][m][n] = (f32x4){0.f, 0.f, 0.f, 0.f};
.LBB0_1406:
	s_add_u32 s78, s66, 0x100
	v_mov_b32_e32 v0, 0
	s_addc_u32 s79, s67, 0
	s_mov_b32 s80, -2
	v_mov_b32_e32 v1, v0
	v_mov_b32_e32 v2, v0
	v_mov_b32_e32 v3, v0
	v_mov_b32_e32 v4, v0
	v_mov_b32_e32 v5, v0
	v_mov_b32_e32 v6, v0
	v_mov_b32_e32 v7, v0
	v_mov_b32_e32 v16, v0
	v_mov_b32_e32 v17, v0
	v_mov_b32_e32 v18, v0
	v_mov_b32_e32 v19, v0
	v_mov_b32_e32 v20, v0
	v_mov_b32_e32 v21, v0
	v_mov_b32_e32 v22, v0
	v_mov_b32_e32 v23, v0
	v_mov_b32_e32 v32, v0
	v_mov_b32_e32 v33, v0
	v_mov_b32_e32 v34, v0
	v_mov_b32_e32 v35, v0
	v_mov_b32_e32 v36, v0
	v_mov_b32_e32 v37, v0
	v_mov_b32_e32 v38, v0
	v_mov_b32_e32 v39, v0
	v_mov_b32_e32 v48, v0
	v_mov_b32_e32 v49, v0
	v_mov_b32_e32 v50, v0
	v_mov_b32_e32 v51, v0
	v_mov_b32_e32 v52, v0
	v_mov_b32_e32 v53, v0
	v_mov_b32_e32 v54, v0
	v_mov_b32_e32 v55, v0
	v_mov_b32_e32 v8, v0
	v_mov_b32_e32 v9, v0
	v_mov_b32_e32 v10, v0
	v_mov_b32_e32 v11, v0
	v_mov_b32_e32 v12, v0
	v_mov_b32_e32 v13, v0
	v_mov_b32_e32 v14, v0
	v_mov_b32_e32 v15, v0
	v_mov_b32_e32 v24, v0
	v_mov_b32_e32 v25, v0
	v_mov_b32_e32 v26, v0
	v_mov_b32_e32 v27, v0
	v_mov_b32_e32 v28, v0
	v_mov_b32_e32 v29, v0
	v_mov_b32_e32 v30, v0
	v_mov_b32_e32 v31, v0
	v_mov_b32_e32 v40, v0
	v_mov_b32_e32 v41, v0
	v_mov_b32_e32 v42, v0
	v_mov_b32_e32 v43, v0
	v_mov_b32_e32 v44, v0
	v_mov_b32_e32 v45, v0
	v_mov_b32_e32 v46, v0
	v_mov_b32_e32 v47, v0
	v_mov_b32_e32 v56, v0
	v_mov_b32_e32 v57, v0
	v_mov_b32_e32 v58, v0
	v_mov_b32_e32 v59, v0
	v_mov_b32_e32 v60, v0
	v_mov_b32_e32 v61, v0
	v_mov_b32_e32 v62, v0
	v_mov_b32_e32 v63, v0
	v_mov_b32_e32 v64, v0
	v_mov_b32_e32 v65, v0
	v_mov_b32_e32 v66, v0
	v_mov_b32_e32 v67, v0
	v_mov_b32_e32 v68, v0
	v_mov_b32_e32 v69, v0
	v_mov_b32_e32 v70, v0
	v_mov_b32_e32 v71, v0
	v_mov_b32_e32 v80, v0
	v_mov_b32_e32 v81, v0
	v_mov_b32_e32 v82, v0
	v_mov_b32_e32 v83, v0
	v_mov_b32_e32 v84, v0
	v_mov_b32_e32 v85, v0
	v_mov_b32_e32 v86, v0
	v_mov_b32_e32 v87, v0
	v_mov_b32_e32 v96, v0
	v_mov_b32_e32 v97, v0
	v_mov_b32_e32 v98, v0
	v_mov_b32_e32 v99, v0
	v_mov_b32_e32 v100, v0
	v_mov_b32_e32 v101, v0
	v_mov_b32_e32 v102, v0
	v_mov_b32_e32 v103, v0
	v_mov_b32_e32 v112, v0
	v_mov_b32_e32 v113, v0
	v_mov_b32_e32 v114, v0
	v_mov_b32_e32 v115, v0
	v_mov_b32_e32 v116, v0
	v_mov_b32_e32 v117, v0
	v_mov_b32_e32 v118, v0
	v_mov_b32_e32 v119, v0
	v_mov_b32_e32 v72, v0
	v_mov_b32_e32 v73, v0
	v_mov_b32_e32 v74, v0
	v_mov_b32_e32 v75, v0
	v_mov_b32_e32 v76, v0
	v_mov_b32_e32 v77, v0
	v_mov_b32_e32 v78, v0
	v_mov_b32_e32 v79, v0
	v_mov_b32_e32 v88, v0
	v_mov_b32_e32 v89, v0
	v_mov_b32_e32 v90, v0
	v_mov_b32_e32 v91, v0
	v_mov_b32_e32 v92, v0
	v_mov_b32_e32 v93, v0
	v_mov_b32_e32 v94, v0
	v_mov_b32_e32 v95, v0
	v_mov_b32_e32 v104, v0
	v_mov_b32_e32 v105, v0
	v_mov_b32_e32 v106, v0
	v_mov_b32_e32 v107, v0
	v_mov_b32_e32 v108, v0
	v_mov_b32_e32 v109, v0
	v_mov_b32_e32 v110, v0
	v_mov_b32_e32 v111, v0
	v_mov_b32_e32 v120, v0
	v_mov_b32_e32 v121, v0
	v_mov_b32_e32 v122, v0
	v_mov_b32_e32 v123, v0
	v_mov_b32_e32 v124, v0
	v_mov_b32_e32 v125, v0
	v_mov_b32_e32 v126, v0
	v_mov_b32_e32 v127, v0
	v_lshl_add_u32 v252, s10, 8, v175
	v_lshlrev_b32_e32 v252, 1, v252
	v_ashrrev_i32_e32 v253, 31, v252
	v_lshl_add_u64 v[252:253], v[252:253], 2, s[62:63]
	global_load_dword v244, v[252:253], off
	global_load_dword v245, v[252:253], off offset:128
	global_load_dword v246, v[252:253], off offset:256
	global_load_dword v247, v[252:253], off offset:384
	global_load_dword v248, v[252:253], off offset:1024
	global_load_dword v249, v[252:253], off offset:1152
	global_load_dword v250, v[252:253], off offset:1280
	global_load_dword v251, v[252:253], off offset:1408

.LBB0_1410:
	v_lshl_add_u32 v172, s10, 8, v175
	v_lshlrev_b32_e32 v150, 1, v172
	v_ashrrev_i32_e32 v151, 31, v150
	v_lshl_add_u64 v[150:151], v[150:151], 2, s[62:63]
	v_mov_b32_e32 v150, v244
	s_lshl_b32 s58, s77, 8
	v_or_b32_e32 v166, 16, v172
	v_or_b32_e32 v162, 32, v172
	v_or_b32_e32 v158, 48, v172
	v_add_u32_e32 v156, 0x80, v172
	s_mov_b64 s[56:57], -1
	s_cmp_gt_i32 s77, 3
	v_add_u32_e32 v154, 0x90, v172
	v_add_u32_e32 v152, 0xa0, v172
	v_lshlrev_b32_e32 v170, 1, v166
	v_lshlrev_b32_e32 v168, 1, v162
	v_lshlrev_b32_e32 v164, 1, v158
	v_lshlrev_b32_e32 v160, 1, v156
	v_mul_f32_e32 v174, 0x3dd53b94, v150
	v_add_u32_e32 v150, 0xb0, v172
	s_cbranch_scc0 .LBB0_1413
	v_ashrrev_i32_e32 v173, 31, v172
	v_lshlrev_b64 v[176:177], 7, v[172:173]
	v_lshl_add_u64 v[192:193], v[140:141], 0, v[176:177]
	global_load_dwordx4 v[184:187], v[192:193], off
	v_lshl_add_u64 v[194:195], v[138:139], 0, v[176:177]
	global_load_dwordx4 v[188:191], v[194:195], off
	s_add_i32 s10, s70, s58
	v_mov_b64_e32 v[176:177], s[40:41]
	v_pk_mul_f32 v[200:201], v[118:119], v[174:175] op_sel_hi:[1,0]
	v_pk_mul_f32 v[202:203], v[116:117], v[174:175] op_sel_hi:[1,0]
	v_pk_mul_f32 v[196:197], v[126:127], v[174:175] op_sel_hi:[1,0]
	v_pk_mul_f32 v[198:199], v[124:125], v[174:175] op_sel_hi:[1,0]
	v_mad_i64_i32 v[204:205], s[34:35], v172, s73, v[176:177]
	s_lshl_b64 s[56:57], s[10:11], 1
	v_lshl_add_u64 v[204:205], v[204:205], 0, s[56:57]
	v_lshl_add_u64 v[204:205], v[204:205], 0, v[136:137]
	v_ashrrev_i32_e32 v171, 31, v170
	v_ashrrev_i32_e32 v167, 31, v166
	v_ashrrev_i32_e32 v169, 31, v168
	v_ashrrev_i32_e32 v163, 31, v162
	v_ashrrev_i32_e32 v165, 31, v164
	v_ashrrev_i32_e32 v159, 31, v158
	v_ashrrev_i32_e32 v161, 31, v160
	v_ashrrev_i32_e32 v157, 31, v156
	v_ashrrev_i32_e32 v155, 31, v154
	v_ashrrev_i32_e32 v153, 31, v152
	s_waitcnt vmcnt(1)
	v_pk_mul_f32 v[206:207], v[200:201], v[186:187]
	v_pk_mul_f32 v[208:209], v[202:203], v[184:185]
	v_pk_mul_f32 v[186:187], v[196:197], v[186:187]
	v_pk_mul_f32 v[184:185], v[198:199], v[184:185]
	s_waitcnt vmcnt(0)
	v_pk_fma_f32 v[196:197], v[196:197], v[190:191], v[206:207] neg_lo:[0,0,1] neg_hi:[0,0,1]
	v_pk_fma_f32 v[198:199], v[198:199], v[188:189], v[208:209] neg_lo:[0,0,1] neg_hi:[0,0,1]
	v_pk_fma_f32 v[186:187], v[200:201], v[190:191], v[186:187]
	v_pk_fma_f32 v[184:185], v[202:203], v[188:189], v[184:185]
	v_cvt_pk_bf16_f32 v188, v198, v199
	v_cvt_pk_bf16_f32 v189, v196, v197
	v_cvt_pk_bf16_f32 v184, v184, v185
	v_cvt_pk_bf16_f32 v185, v186, v187
	global_store_dwordx2 v[204:205], v[188:189], off offset:2048
	global_store_dwordx2 v[204:205], v[184:185], off offset:2112
	global_load_dwordx4 v[184:187], v[192:193], off offset:16
	s_nop 0
	global_load_dwordx4 v[188:191], v[194:195], off offset:16
	v_pk_mul_f32 v[196:197], v[114:115], v[174:175] op_sel_hi:[1,0]
	v_pk_mul_f32 v[198:199], v[112:113], v[174:175] op_sel_hi:[1,0]
	v_pk_mul_f32 v[192:193], v[122:123], v[174:175] op_sel_hi:[1,0]
	v_pk_mul_f32 v[194:195], v[120:121], v[174:175] op_sel_hi:[1,0]
	v_lshl_add_u64 v[200:201], v[170:171], 2, s[62:63]
	s_waitcnt vmcnt(1)
	v_pk_mul_f32 v[202:203], v[196:197], v[186:187]
	v_pk_mul_f32 v[206:207], v[198:199], v[184:185]
	v_pk_mul_f32 v[186:187], v[192:193], v[186:187]
	v_pk_mul_f32 v[184:185], v[194:195], v[184:185]
	s_waitcnt vmcnt(0)
	v_pk_fma_f32 v[192:193], v[192:193], v[190:191], v[202:203] neg_lo:[0,0,1] neg_hi:[0,0,1]
	v_pk_fma_f32 v[194:195], v[194:195], v[188:189], v[206:207] neg_lo:[0,0,1] neg_hi:[0,0,1]
	v_pk_fma_f32 v[186:187], v[196:197], v[190:191], v[186:187]
	v_pk_fma_f32 v[184:185], v[198:199], v[188:189], v[184:185]
	v_cvt_pk_bf16_f32 v188, v194, v195
	v_cvt_pk_bf16_f32 v189, v192, v193
	v_cvt_pk_bf16_f32 v184, v184, v185
	v_cvt_pk_bf16_f32 v185, v186, v187
	global_store_dwordx2 v[204:205], v[188:189], off offset:2056
	global_store_dwordx2 v[204:205], v[184:185], off offset:2120
	global_load_dword v151, v[200:201], off
	v_lshlrev_b64 v[188:189], 7, v[166:167]
	v_lshl_add_u64 v[192:193], v[140:141], 0, v[188:189]
	global_load_dwordx4 v[184:187], v[192:193], off
	v_lshl_add_u64 v[194:195], v[138:139], 0, v[188:189]
	global_load_dwordx4 v[188:191], v[194:195], off
	v_mad_i64_i32 v[196:197], s[34:35], v166, s73, v[176:177]
	v_lshl_add_u64 v[196:197], v[196:197], 0, s[56:57]
	v_lshl_add_u64 v[196:197], v[196:197], 0, v[136:137]
	s_waitcnt vmcnt(2)
	v_mul_f32_e32 v198, 0x3dd53b94, v151
	v_pk_mul_f32 v[204:205], v[102:103], v[198:199] op_sel_hi:[1,0]
	v_pk_mul_f32 v[206:207], v[100:101], v[198:199] op_sel_hi:[1,0]
	v_pk_mul_f32 v[200:201], v[108:109], v[198:199] op_sel_hi:[1,0]
	v_pk_mul_f32 v[202:203], v[110:111], v[198:199] op_sel_hi:[1,0]
	s_waitcnt vmcnt(1)
	v_pk_mul_f32 v[208:209], v[184:185], v[206:207]
	v_pk_mul_f32 v[210:211], v[186:187], v[204:205]
	s_waitcnt vmcnt(0)
	v_pk_mul_f32 v[206:207], v[188:189], v[206:207]
	v_pk_mul_f32 v[204:205], v[190:191], v[204:205]
	v_pk_fma_f32 v[190:191], v[190:191], v[202:203], v[210:211] neg_lo:[0,0,1] neg_hi:[0,0,1]
	v_pk_fma_f32 v[188:189], v[188:189], v[200:201], v[208:209] neg_lo:[0,0,1] neg_hi:[0,0,1]
	v_pk_fma_f32 v[186:187], v[186:187], v[202:203], v[204:205]
	v_pk_fma_f32 v[184:185], v[184:185], v[200:201], v[206:207]
	v_cvt_pk_bf16_f32 v188, v188, v189
	v_cvt_pk_bf16_f32 v189, v190, v191
	v_cvt_pk_bf16_f32 v184, v184, v185
	v_cvt_pk_bf16_f32 v185, v186, v187
	global_store_dwordx2 v[196:197], v[188:189], off offset:2048
	global_store_dwordx2 v[196:197], v[184:185], off offset:2112
	global_load_dwordx4 v[184:187], v[192:193], off offset:16
	s_nop 0
	global_load_dwordx4 v[188:191], v[194:195], off offset:16
	v_pk_mul_f32 v[194:195], v[104:105], v[198:199] op_sel_hi:[1,0]
	v_pk_mul_f32 v[200:201], v[106:107], v[198:199] op_sel_hi:[1,0]
	v_pk_mul_f32 v[202:203], v[98:99], v[198:199] op_sel_hi:[1,0]
	v_pk_mul_f32 v[198:199], v[96:97], v[198:199] op_sel_hi:[1,0]
	v_lshl_add_u64 v[192:193], v[168:169], 2, s[62:63]
	s_waitcnt vmcnt(1)
	v_pk_mul_f32 v[204:205], v[198:199], v[184:185]
	v_pk_mul_f32 v[206:207], v[202:203], v[186:187]
	v_pk_mul_f32 v[184:185], v[194:195], v[184:185]
	v_pk_mul_f32 v[186:187], v[200:201], v[186:187]
	s_waitcnt vmcnt(0)
	v_pk_fma_f32 v[200:201], v[200:201], v[190:191], v[206:207] neg_lo:[0,0,1] neg_hi:[0,0,1]
	v_pk_fma_f32 v[194:195], v[194:195], v[188:189], v[204:205] neg_lo:[0,0,1] neg_hi:[0,0,1]
	v_pk_fma_f32 v[186:187], v[202:203], v[190:191], v[186:187]
	v_pk_fma_f32 v[184:185], v[198:199], v[188:189], v[184:185]
	v_cvt_pk_bf16_f32 v188, v194, v195
	v_cvt_pk_bf16_f32 v189, v200, v201
	v_cvt_pk_bf16_f32 v184, v184, v185
	v_cvt_pk_bf16_f32 v185, v186, v187
	global_store_dwordx2 v[196:197], v[188:189], off offset:2056
	global_store_dwordx2 v[196:197], v[184:185], off offset:2120
	global_load_dword v151, v[192:193], off
	v_lshlrev_b64 v[188:189], 7, v[162:163]
	v_lshl_add_u64 v[192:193], v[140:141], 0, v[188:189]
	global_load_dwordx4 v[184:187], v[192:193], off
	v_lshl_add_u64 v[194:195], v[138:139], 0, v[188:189]
	global_load_dwordx4 v[188:191], v[194:195], off
	v_mad_i64_i32 v[196:197], s[34:35], v162, s73, v[176:177]
	v_lshl_add_u64 v[196:197], v[196:197], 0, s[56:57]
	v_lshl_add_u64 v[196:197], v[196:197], 0, v[136:137]
	s_waitcnt vmcnt(2)
	v_mul_f32_e32 v198, 0x3dd53b94, v151
	v_pk_mul_f32 v[204:205], v[86:87], v[198:199] op_sel_hi:[1,0]
	v_pk_mul_f32 v[206:207], v[84:85], v[198:199] op_sel_hi:[1,0]
	v_pk_mul_f32 v[200:201], v[92:93], v[198:199] op_sel_hi:[1,0]
	v_pk_mul_f32 v[202:203], v[94:95], v[198:199] op_sel_hi:[1,0]
	s_waitcnt vmcnt(1)
	v_pk_mul_f32 v[208:209], v[184:185], v[206:207]
	v_pk_mul_f32 v[210:211], v[186:187], v[204:205]
	s_waitcnt vmcnt(0)
	v_pk_mul_f32 v[206:207], v[188:189], v[206:207]
	v_pk_mul_f32 v[204:205], v[190:191], v[204:205]
	v_pk_fma_f32 v[190:191], v[190:191], v[202:203], v[210:211] neg_lo:[0,0,1] neg_hi:[0,0,1]
	v_pk_fma_f32 v[188:189], v[188:189], v[200:201], v[208:209] neg_lo:[0,0,1] neg_hi:[0,0,1]
	v_pk_fma_f32 v[186:187], v[186:187], v[202:203], v[204:205]
	v_pk_fma_f32 v[184:185], v[184:185], v[200:201], v[206:207]
	v_cvt_pk_bf16_f32 v188, v188, v189
	v_cvt_pk_bf16_f32 v189, v190, v191
	v_cvt_pk_bf16_f32 v184, v184, v185
	v_cvt_pk_bf16_f32 v185, v186, v187
	global_store_dwordx2 v[196:197], v[188:189], off offset:2048
	global_store_dwordx2 v[196:197], v[184:185], off offset:2112
	global_load_dwordx4 v[184:187], v[192:193], off offset:16
	s_nop 0
	global_load_dwordx4 v[188:191], v[194:195], off offset:16
	v_pk_mul_f32 v[194:195], v[88:89], v[198:199] op_sel_hi:[1,0]
	v_pk_mul_f32 v[200:201], v[90:91], v[198:199] op_sel_hi:[1,0]
	v_pk_mul_f32 v[202:203], v[82:83], v[198:199] op_sel_hi:[1,0]
	v_pk_mul_f32 v[198:199], v[80:81], v[198:199] op_sel_hi:[1,0]
	v_lshl_add_u64 v[192:193], v[164:165], 2, s[62:63]
	s_waitcnt vmcnt(1)
	v_pk_mul_f32 v[204:205], v[198:199], v[184:185]
	v_pk_mul_f32 v[206:207], v[202:203], v[186:187]
	v_pk_mul_f32 v[184:185], v[194:195], v[184:185]
	v_pk_mul_f32 v[186:187], v[200:201], v[186:187]
	s_waitcnt vmcnt(0)
	v_pk_fma_f32 v[200:201], v[200:201], v[190:191], v[206:207] neg_lo:[0,0,1] neg_hi:[0,0,1]
	v_pk_fma_f32 v[194:195], v[194:195], v[188:189], v[204:205] neg_lo:[0,0,1] neg_hi:[0,0,1]
	v_pk_fma_f32 v[186:187], v[202:203], v[190:191], v[186:187]
	v_pk_fma_f32 v[184:185], v[198:199], v[188:189], v[184:185]
	v_cvt_pk_bf16_f32 v188, v194, v195
	v_cvt_pk_bf16_f32 v189, v200, v201
	v_cvt_pk_bf16_f32 v184, v184, v185
	v_cvt_pk_bf16_f32 v185, v186, v187
	global_store_dwordx2 v[196:197], v[188:189], off offset:2056
	global_store_dwordx2 v[196:197], v[184:185], off offset:2120
	global_load_dword v151, v[192:193], off
	v_lshlrev_b64 v[188:189], 7, v[158:159]
	v_lshl_add_u64 v[192:193], v[140:141], 0, v[188:189]
	global_load_dwordx4 v[184:187], v[192:193], off
	v_lshl_add_u64 v[194:195], v[138:139], 0, v[188:189]
	global_load_dwordx4 v[188:191], v[194:195], off
	v_mad_i64_i32 v[196:197], s[34:35], v158, s73, v[176:177]
	v_lshl_add_u64 v[196:197], v[196:197], 0, s[56:57]
	v_lshl_add_u64 v[196:197], v[196:197], 0, v[136:137]
	s_waitcnt vmcnt(2)
	v_mul_f32_e32 v198, 0x3dd53b94, v151
	v_pk_mul_f32 v[204:205], v[70:71], v[198:199] op_sel_hi:[1,0]
	v_pk_mul_f32 v[206:207], v[68:69], v[198:199] op_sel_hi:[1,0]
	v_pk_mul_f32 v[200:201], v[76:77], v[198:199] op_sel_hi:[1,0]
	v_pk_mul_f32 v[202:203], v[78:79], v[198:199] op_sel_hi:[1,0]
	s_waitcnt vmcnt(1)
	v_pk_mul_f32 v[208:209], v[184:185], v[206:207]
	v_pk_mul_f32 v[210:211], v[186:187], v[204:205]
	s_waitcnt vmcnt(0)
	v_pk_mul_f32 v[206:207], v[188:189], v[206:207]
	v_pk_mul_f32 v[204:205], v[190:191], v[204:205]
	v_pk_fma_f32 v[190:191], v[190:191], v[202:203], v[210:211] neg_lo:[0,0,1] neg_hi:[0,0,1]
	v_pk_fma_f32 v[188:189], v[188:189], v[200:201], v[208:209] neg_lo:[0,0,1] neg_hi:[0,0,1]
	v_pk_fma_f32 v[186:187], v[186:187], v[202:203], v[204:205]
	v_pk_fma_f32 v[184:185], v[184:185], v[200:201], v[206:207]
	v_cvt_pk_bf16_f32 v188, v188, v189
	v_cvt_pk_bf16_f32 v189, v190, v191
	v_cvt_pk_bf16_f32 v184, v184, v185
	v_cvt_pk_bf16_f32 v185, v186, v187
	global_store_dwordx2 v[196:197], v[188:189], off offset:2048
	global_store_dwordx2 v[196:197], v[184:185], off offset:2112
	global_load_dwordx4 v[184:187], v[192:193], off offset:16
	s_nop 0
	global_load_dwordx4 v[188:191], v[194:195], off offset:16
	v_pk_mul_f32 v[194:195], v[72:73], v[198:199] op_sel_hi:[1,0]
	v_pk_mul_f32 v[200:201], v[74:75], v[198:199] op_sel_hi:[1,0]
	v_pk_mul_f32 v[202:203], v[66:67], v[198:199] op_sel_hi:[1,0]
	v_pk_mul_f32 v[198:199], v[64:65], v[198:199] op_sel_hi:[1,0]
	v_lshl_add_u64 v[192:193], v[160:161], 2, s[62:63]
	s_waitcnt vmcnt(1)
	v_pk_mul_f32 v[204:205], v[198:199], v[184:185]
	v_pk_mul_f32 v[206:207], v[202:203], v[186:187]
	v_pk_mul_f32 v[184:185], v[194:195], v[184:185]
	v_pk_mul_f32 v[186:187], v[200:201], v[186:187]
	s_waitcnt vmcnt(0)
	v_pk_fma_f32 v[200:201], v[200:201], v[190:191], v[206:207] neg_lo:[0,0,1] neg_hi:[0,0,1]
	v_pk_fma_f32 v[194:195], v[194:195], v[188:189], v[204:205] neg_lo:[0,0,1] neg_hi:[0,0,1]
	v_pk_fma_f32 v[186:187], v[202:203], v[190:191], v[186:187]
	v_pk_fma_f32 v[184:185], v[198:199], v[188:189], v[184:185]
	v_cvt_pk_bf16_f32 v188, v194, v195
	v_cvt_pk_bf16_f32 v189, v200, v201
	v_cvt_pk_bf16_f32 v184, v184, v185
	v_cvt_pk_bf16_f32 v185, v186, v187
	global_store_dwordx2 v[196:197], v[188:189], off offset:2056
	global_store_dwordx2 v[196:197], v[184:185], off offset:2120
	global_load_dword v151, v[192:193], off
	v_lshlrev_b64 v[188:189], 7, v[156:157]
	v_lshl_add_u64 v[192:193], v[140:141], 0, v[188:189]
	global_load_dwordx4 v[184:187], v[192:193], off
	v_lshl_add_u64 v[194:195], v[138:139], 0, v[188:189]
	global_load_dwordx4 v[188:191], v[194:195], off
	v_mad_i64_i32 v[196:197], s[34:35], v156, s73, v[176:177]
	v_lshl_add_u64 v[196:197], v[196:197], 0, s[56:57]
	v_lshl_add_u64 v[196:197], v[196:197], 0, v[136:137]
	s_waitcnt vmcnt(2)
	v_mul_f32_e32 v198, 0x3dd53b94, v151
	v_pk_mul_f32 v[204:205], v[54:55], v[198:199] op_sel_hi:[1,0]
	v_pk_mul_f32 v[206:207], v[52:53], v[198:199] op_sel_hi:[1,0]
	v_pk_mul_f32 v[200:201], v[60:61], v[198:199] op_sel_hi:[1,0]
	v_pk_mul_f32 v[202:203], v[62:63], v[198:199] op_sel_hi:[1,0]
	s_waitcnt vmcnt(1)
	v_pk_mul_f32 v[208:209], v[184:185], v[206:207]
	v_pk_mul_f32 v[210:211], v[186:187], v[204:205]
	s_waitcnt vmcnt(0)
	v_pk_mul_f32 v[206:207], v[188:189], v[206:207]
	v_pk_mul_f32 v[204:205], v[190:191], v[204:205]
	v_pk_fma_f32 v[190:191], v[190:191], v[202:203], v[210:211] neg_lo:[0,0,1] neg_hi:[0,0,1]
	v_pk_fma_f32 v[188:189], v[188:189], v[200:201], v[208:209] neg_lo:[0,0,1] neg_hi:[0,0,1]
	v_pk_fma_f32 v[186:187], v[186:187], v[202:203], v[204:205]
	v_pk_fma_f32 v[184:185], v[184:185], v[200:201], v[206:207]
	v_cvt_pk_bf16_f32 v188, v188, v189
	v_cvt_pk_bf16_f32 v189, v190, v191
	v_cvt_pk_bf16_f32 v184, v184, v185
	v_cvt_pk_bf16_f32 v185, v186, v187
	global_store_dwordx2 v[196:197], v[188:189], off offset:2048
	global_store_dwordx2 v[196:197], v[184:185], off offset:2112
	global_load_dwordx4 v[184:187], v[192:193], off offset:16
	s_nop 0
	global_load_dwordx4 v[188:191], v[194:195], off offset:16
	v_pk_mul_f32 v[194:195], v[56:57], v[198:199] op_sel_hi:[1,0]
	v_pk_mul_f32 v[200:201], v[58:59], v[198:199] op_sel_hi:[1,0]
	v_pk_mul_f32 v[202:203], v[50:51], v[198:199] op_sel_hi:[1,0]
	v_pk_mul_f32 v[198:199], v[48:49], v[198:199] op_sel_hi:[1,0]
	v_lshlrev_b32_e32 v192, 1, v154
	v_ashrrev_i32_e32 v193, 31, v192
	v_lshl_add_u64 v[192:193], v[192:193], 2, s[62:63]
	s_waitcnt vmcnt(1)
	v_pk_mul_f32 v[204:205], v[198:199], v[184:185]
	v_pk_mul_f32 v[206:207], v[202:203], v[186:187]
	v_pk_mul_f32 v[184:185], v[194:195], v[184:185]
	v_pk_mul_f32 v[186:187], v[200:201], v[186:187]
	s_waitcnt vmcnt(0)
	v_pk_fma_f32 v[200:201], v[200:201], v[190:191], v[206:207] neg_lo:[0,0,1] neg_hi:[0,0,1]
	v_pk_fma_f32 v[194:195], v[194:195], v[188:189], v[204:205] neg_lo:[0,0,1] neg_hi:[0,0,1]
	v_pk_fma_f32 v[186:187], v[202:203], v[190:191], v[186:187]
	v_pk_fma_f32 v[184:185], v[198:199], v[188:189], v[184:185]
	v_cvt_pk_bf16_f32 v188, v194, v195
	v_cvt_pk_bf16_f32 v189, v200, v201
	v_cvt_pk_bf16_f32 v184, v184, v185
	v_cvt_pk_bf16_f32 v185, v186, v187
	global_store_dwordx2 v[196:197], v[188:189], off offset:2056
	global_store_dwordx2 v[196:197], v[184:185], off offset:2120
	global_load_dword v151, v[192:193], off
	v_lshlrev_b64 v[188:189], 7, v[154:155]
	v_lshl_add_u64 v[192:193], v[140:141], 0, v[188:189]
	global_load_dwordx4 v[184:187], v[192:193], off
	v_lshl_add_u64 v[194:195], v[138:139], 0, v[188:189]
	global_load_dwordx4 v[188:191], v[194:195], off
	v_mad_i64_i32 v[196:197], s[34:35], v154, s73, v[176:177]
	v_lshl_add_u64 v[196:197], v[196:197], 0, s[56:57]
	v_lshl_add_u64 v[196:197], v[196:197], 0, v[136:137]
	s_waitcnt vmcnt(2)
	v_mul_f32_e32 v198, 0x3dd53b94, v151
	v_pk_mul_f32 v[204:205], v[38:39], v[198:199] op_sel_hi:[1,0]
	v_pk_mul_f32 v[206:207], v[36:37], v[198:199] op_sel_hi:[1,0]
	v_pk_mul_f32 v[200:201], v[44:45], v[198:199] op_sel_hi:[1,0]
	v_pk_mul_f32 v[202:203], v[46:47], v[198:199] op_sel_hi:[1,0]
	s_waitcnt vmcnt(1)
	v_pk_mul_f32 v[208:209], v[184:185], v[206:207]
	v_pk_mul_f32 v[210:211], v[186:187], v[204:205]
	s_waitcnt vmcnt(0)
	v_pk_mul_f32 v[206:207], v[188:189], v[206:207]
	v_pk_mul_f32 v[204:205], v[190:191], v[204:205]
	v_pk_fma_f32 v[190:191], v[190:191], v[202:203], v[210:211] neg_lo:[0,0,1] neg_hi:[0,0,1]
	v_pk_fma_f32 v[188:189], v[188:189], v[200:201], v[208:209] neg_lo:[0,0,1] neg_hi:[0,0,1]
	v_pk_fma_f32 v[186:187], v[186:187], v[202:203], v[204:205]
	v_pk_fma_f32 v[184:185], v[184:185], v[200:201], v[206:207]
	v_cvt_pk_bf16_f32 v188, v188, v189
	v_cvt_pk_bf16_f32 v189, v190, v191
	v_cvt_pk_bf16_f32 v184, v184, v185
	v_cvt_pk_bf16_f32 v185, v186, v187
	global_store_dwordx2 v[196:197], v[188:189], off offset:2048
	global_store_dwordx2 v[196:197], v[184:185], off offset:2112
	global_load_dwordx4 v[184:187], v[192:193], off offset:16
	s_nop 0
	global_load_dwordx4 v[188:191], v[194:195], off offset:16
	v_pk_mul_f32 v[194:195], v[40:41], v[198:199] op_sel_hi:[1,0]
	v_pk_mul_f32 v[200:201], v[42:43], v[198:199] op_sel_hi:[1,0]
	v_pk_mul_f32 v[202:203], v[34:35], v[198:199] op_sel_hi:[1,0]
	v_pk_mul_f32 v[198:199], v[32:33], v[198:199] op_sel_hi:[1,0]
	v_lshlrev_b32_e32 v192, 1, v152
	v_ashrrev_i32_e32 v193, 31, v192
	v_lshl_add_u64 v[192:193], v[192:193], 2, s[62:63]
	s_waitcnt vmcnt(1)
	v_pk_mul_f32 v[204:205], v[198:199], v[184:185]
	v_pk_mul_f32 v[206:207], v[202:203], v[186:187]
	v_pk_mul_f32 v[184:185], v[194:195], v[184:185]
	v_pk_mul_f32 v[186:187], v[200:201], v[186:187]
	s_waitcnt vmcnt(0)
	v_pk_fma_f32 v[200:201], v[200:201], v[190:191], v[206:207] neg_lo:[0,0,1] neg_hi:[0,0,1]
	v_pk_fma_f32 v[194:195], v[194:195], v[188:189], v[204:205] neg_lo:[0,0,1] neg_hi:[0,0,1]
	v_pk_fma_f32 v[186:187], v[202:203], v[190:191], v[186:187]
	v_pk_fma_f32 v[184:185], v[198:199], v[188:189], v[184:185]
	v_cvt_pk_bf16_f32 v188, v194, v195
	v_cvt_pk_bf16_f32 v189, v200, v201
	v_cvt_pk_bf16_f32 v184, v184, v185
	v_cvt_pk_bf16_f32 v185, v186, v187
	global_store_dwordx2 v[196:197], v[188:189], off offset:2056
	global_store_dwordx2 v[196:197], v[184:185], off offset:2120
	global_load_dword v151, v[192:193], off
	v_lshlrev_b64 v[188:189], 7, v[152:153]
	v_lshl_add_u64 v[192:193], v[140:141], 0, v[188:189]
	global_load_dwordx4 v[184:187], v[192:193], off
	v_lshl_add_u64 v[194:195], v[138:139], 0, v[188:189]
	global_load_dwordx4 v[188:191], v[194:195], off
	v_mad_i64_i32 v[196:197], s[34:35], v152, s73, v[176:177]
	v_lshl_add_u64 v[196:197], v[196:197], 0, s[56:57]
	v_lshl_add_u64 v[196:197], v[196:197], 0, v[136:137]
	v_mad_i64_i32 v[176:177], s[34:35], v150, s73, v[176:177]
	v_lshl_add_u64 v[176:177], v[176:177], 0, s[56:57]
	v_lshl_add_u64 v[176:177], v[176:177], 0, v[136:137]
	s_waitcnt vmcnt(2)
	v_mul_f32_e32 v198, 0x3dd53b94, v151
	v_pk_mul_f32 v[204:205], v[22:23], v[198:199] op_sel_hi:[1,0]
	v_pk_mul_f32 v[206:207], v[20:21], v[198:199] op_sel_hi:[1,0]
	v_pk_mul_f32 v[200:201], v[28:29], v[198:199] op_sel_hi:[1,0]
	v_pk_mul_f32 v[202:203], v[30:31], v[198:199] op_sel_hi:[1,0]
	s_waitcnt vmcnt(1)
	v_pk_mul_f32 v[208:209], v[184:185], v[206:207]
	v_pk_mul_f32 v[210:211], v[186:187], v[204:205]
	s_waitcnt vmcnt(0)
	v_pk_mul_f32 v[206:207], v[188:189], v[206:207]
	v_pk_mul_f32 v[204:205], v[190:191], v[204:205]
	v_pk_fma_f32 v[190:191], v[190:191], v[202:203], v[210:211] neg_lo:[0,0,1] neg_hi:[0,0,1]
	v_pk_fma_f32 v[188:189], v[188:189], v[200:201], v[208:209] neg_lo:[0,0,1] neg_hi:[0,0,1]
	v_pk_fma_f32 v[186:187], v[186:187], v[202:203], v[204:205]
	v_pk_fma_f32 v[184:185], v[184:185], v[200:201], v[206:207]
	v_cvt_pk_bf16_f32 v188, v188, v189
	v_cvt_pk_bf16_f32 v189, v190, v191
	v_cvt_pk_bf16_f32 v184, v184, v185
	v_cvt_pk_bf16_f32 v185, v186, v187
	global_store_dwordx2 v[196:197], v[188:189], off offset:2048
	global_store_dwordx2 v[196:197], v[184:185], off offset:2112
	global_load_dwordx4 v[184:187], v[192:193], off offset:16
	s_nop 0
	global_load_dwordx4 v[188:191], v[194:195], off offset:16
	v_pk_mul_f32 v[194:195], v[24:25], v[198:199] op_sel_hi:[1,0]
	v_pk_mul_f32 v[200:201], v[26:27], v[198:199] op_sel_hi:[1,0]
	v_pk_mul_f32 v[202:203], v[18:19], v[198:199] op_sel_hi:[1,0]
	v_pk_mul_f32 v[198:199], v[16:17], v[198:199] op_sel_hi:[1,0]
	v_lshlrev_b32_e32 v192, 1, v150
	v_ashrrev_i32_e32 v193, 31, v192
	v_lshl_add_u64 v[192:193], v[192:193], 2, s[62:63]
	v_ashrrev_i32_e32 v151, 31, v150
	s_waitcnt vmcnt(1)
	v_pk_mul_f32 v[204:205], v[198:199], v[184:185]
	v_pk_mul_f32 v[206:207], v[202:203], v[186:187]
	v_pk_mul_f32 v[184:185], v[194:195], v[184:185]
	v_pk_mul_f32 v[186:187], v[200:201], v[186:187]
	s_waitcnt vmcnt(0)
	v_pk_fma_f32 v[200:201], v[200:201], v[190:191], v[206:207] neg_lo:[0,0,1] neg_hi:[0,0,1]
	v_pk_fma_f32 v[194:195], v[194:195], v[188:189], v[204:205] neg_lo:[0,0,1] neg_hi:[0,0,1]
	v_pk_fma_f32 v[186:187], v[202:203], v[190:191], v[186:187]
	v_pk_fma_f32 v[184:185], v[198:199], v[188:189], v[184:185]
	v_cvt_pk_bf16_f32 v188, v194, v195
	v_cvt_pk_bf16_f32 v189, v200, v201
	v_cvt_pk_bf16_f32 v184, v184, v185
	v_cvt_pk_bf16_f32 v185, v186, v187
	global_store_dwordx2 v[196:197], v[188:189], off offset:2056
	global_store_dwordx2 v[196:197], v[184:185], off offset:2120
	global_load_dword v153, v[192:193], off
	v_lshlrev_b64 v[188:189], 7, v[150:151]
	v_lshl_add_u64 v[192:193], v[140:141], 0, v[188:189]
	global_load_dwordx4 v[184:187], v[192:193], off
	v_lshl_add_u64 v[194:195], v[138:139], 0, v[188:189]
	global_load_dwordx4 v[188:191], v[194:195], off
	s_waitcnt vmcnt(2)
	v_mul_f32_e32 v196, 0x3dd53b94, v153
	v_pk_mul_f32 v[202:203], v[6:7], v[196:197] op_sel_hi:[1,0]
	v_pk_mul_f32 v[204:205], v[4:5], v[196:197] op_sel_hi:[1,0]
	v_pk_mul_f32 v[198:199], v[12:13], v[196:197] op_sel_hi:[1,0]
	v_pk_mul_f32 v[200:201], v[14:15], v[196:197] op_sel_hi:[1,0]
	s_waitcnt vmcnt(1)
	v_pk_mul_f32 v[206:207], v[184:185], v[204:205]
	v_pk_mul_f32 v[208:209], v[186:187], v[202:203]
	s_waitcnt vmcnt(0)
	v_pk_mul_f32 v[204:205], v[188:189], v[204:205]
	v_pk_mul_f32 v[202:203], v[190:191], v[202:203]
	v_pk_fma_f32 v[190:191], v[190:191], v[200:201], v[208:209] neg_lo:[0,0,1] neg_hi:[0,0,1]
	v_pk_fma_f32 v[188:189], v[188:189], v[198:199], v[206:207] neg_lo:[0,0,1] neg_hi:[0,0,1]
	v_pk_fma_f32 v[186:187], v[186:187], v[200:201], v[202:203]
	v_pk_fma_f32 v[184:185], v[184:185], v[198:199], v[204:205]
	v_cvt_pk_bf16_f32 v188, v188, v189
	v_cvt_pk_bf16_f32 v189, v190, v191
	v_cvt_pk_bf16_f32 v184, v184, v185
	v_cvt_pk_bf16_f32 v185, v186, v187
	global_store_dwordx2 v[176:177], v[188:189], off offset:2048
	global_store_dwordx2 v[176:177], v[184:185], off offset:2112
	global_load_dwordx4 v[184:187], v[192:193], off offset:16
	s_nop 0
	global_load_dwordx4 v[188:191], v[194:195], off offset:16
	v_pk_mul_f32 v[192:193], v[8:9], v[196:197] op_sel_hi:[1,0]
	v_pk_mul_f32 v[194:195], v[10:11], v[196:197] op_sel_hi:[1,0]
	v_pk_mul_f32 v[198:199], v[2:3], v[196:197] op_sel_hi:[1,0]
	v_pk_mul_f32 v[196:197], v[0:1], v[196:197] op_sel_hi:[1,0]
	s_waitcnt vmcnt(1)
	v_pk_mul_f32 v[202:203], v[198:199], v[186:187]
	v_pk_mul_f32 v[200:201], v[196:197], v[184:185]
	v_pk_mul_f32 v[184:185], v[192:193], v[184:185]
	v_pk_mul_f32 v[186:187], v[194:195], v[186:187]
	s_waitcnt vmcnt(0)
	v_pk_fma_f32 v[194:195], v[194:195], v[190:191], v[202:203] neg_lo:[0,0,1] neg_hi:[0,0,1]
	v_pk_fma_f32 v[192:193], v[192:193], v[188:189], v[200:201] neg_lo:[0,0,1] neg_hi:[0,0,1]
	v_pk_fma_f32 v[186:187], v[198:199], v[190:191], v[186:187]
	v_pk_fma_f32 v[184:185], v[196:197], v[188:189], v[184:185]
	v_cvt_pk_bf16_f32 v188, v192, v193
	v_cvt_pk_bf16_f32 v189, v194, v195
	v_cvt_pk_bf16_f32 v184, v184, v185
	v_cvt_pk_bf16_f32 v185, v186, v187
	global_store_dwordx2 v[176:177], v[188:189], off offset:2056
	global_store_dwordx2 v[176:177], v[184:185], off offset:2120
	s_cbranch_execz .LBB0_1414

.LBB0_1414:
	v_or_b32_e32 v176, s58, v179
	v_pk_mul_f32 v[126:127], v[126:127], v[174:175] op_sel_hi:[1,0]
	v_pk_mul_f32 v[124:125], v[124:125], v[174:175] op_sel_hi:[1,0]
	v_pk_mul_f32 v[120:121], v[120:121], v[174:175] op_sel_hi:[1,0]
	v_ashrrev_i32_e32 v177, 31, v176
	v_pk_mul_f32 v[122:123], v[122:123], v[174:175] op_sel_hi:[1,0]
	v_cvt_pk_bf16_f32 v124, v124, v125
	v_cvt_pk_bf16_f32 v125, v126, v127
	v_cvt_pk_bf16_f32 v126, v120, v121
	v_mov_b64_e32 v[120:121], s[40:41]
	v_cvt_pk_bf16_f32 v127, v122, v123
	v_mad_i64_i32 v[172:173], s[34:35], v172, s73, v[120:121]
	v_lshlrev_b64 v[122:123], 1, v[176:177]
	v_lshl_add_u64 v[172:173], v[172:173], 0, v[122:123]
	global_store_dwordx4 v[172:173], v[124:127], off
	v_pk_mul_f32 v[118:119], v[118:119], v[174:175] op_sel_hi:[1,0]
	v_pk_mul_f32 v[116:117], v[116:117], v[174:175] op_sel_hi:[1,0]
	v_pk_mul_f32 v[124:125], v[114:115], v[174:175] op_sel_hi:[1,0]
	v_pk_mul_f32 v[114:115], v[112:113], v[174:175] op_sel_hi:[1,0]
	v_cvt_pk_bf16_f32 v112, v116, v117
	v_cvt_pk_bf16_f32 v113, v118, v119
	v_cvt_pk_bf16_f32 v114, v114, v115
	v_cvt_pk_bf16_f32 v115, v124, v125
	v_ashrrev_i32_e32 v171, 31, v170
	global_store_dwordx4 v[172:173], v[112:115], off offset:256
	v_ashrrev_i32_e32 v169, 31, v168
	v_ashrrev_i32_e32 v165, 31, v164
	v_lshl_add_u64 v[112:113], v[170:171], 2, s[62:63]
	s_nop 1
	v_mov_b32_e32 v116, v245
	v_mad_i64_i32 v[112:113], s[34:35], v166, s73, v[120:121]
	v_lshl_add_u64 v[112:113], v[112:113], 0, v[122:123]
	v_lshl_add_u64 v[114:115], v[168:169], 2, s[62:63]
	v_ashrrev_i32_e32 v161, 31, v160
	v_mul_f32_e32 v116, 0x3dd53b94, v116
	v_pk_mul_f32 v[110:111], v[110:111], v[116:117] op_sel_hi:[1,0]
	v_pk_mul_f32 v[108:109], v[108:109], v[116:117] op_sel_hi:[1,0]
	v_pk_mul_f32 v[106:107], v[106:107], v[116:117] op_sel_hi:[1,0]
	v_pk_mul_f32 v[104:105], v[104:105], v[116:117] op_sel_hi:[1,0]
	v_pk_mul_f32 v[102:103], v[102:103], v[116:117] op_sel_hi:[1,0]
	v_pk_mul_f32 v[100:101], v[100:101], v[116:117] op_sel_hi:[1,0]
	v_pk_mul_f32 v[118:119], v[98:99], v[116:117] op_sel_hi:[1,0]
	v_pk_mul_f32 v[116:117], v[96:97], v[116:117] op_sel_hi:[1,0]
	v_cvt_pk_bf16_f32 v96, v108, v109
	v_cvt_pk_bf16_f32 v97, v110, v111
	v_cvt_pk_bf16_f32 v98, v104, v105
	v_cvt_pk_bf16_f32 v99, v106, v107
	v_cvt_pk_bf16_f32 v100, v100, v101
	v_cvt_pk_bf16_f32 v101, v102, v103
	v_cvt_pk_bf16_f32 v102, v116, v117
	v_cvt_pk_bf16_f32 v103, v118, v119
	global_store_dwordx4 v[112:113], v[96:99], off
	global_store_dwordx4 v[112:113], v[100:103], off offset:256
	s_nop 1
	v_mov_b32_e32 v100, v246
	v_mad_i64_i32 v[96:97], s[34:35], v162, s73, v[120:121]
	v_lshl_add_u64 v[96:97], v[96:97], 0, v[122:123]
	v_lshl_add_u64 v[98:99], v[164:165], 2, s[62:63]
	v_mul_f32_e32 v100, 0x3dd53b94, v100
	v_pk_mul_f32 v[94:95], v[94:95], v[100:101] op_sel_hi:[1,0]
	v_pk_mul_f32 v[92:93], v[92:93], v[100:101] op_sel_hi:[1,0]
	v_pk_mul_f32 v[90:91], v[90:91], v[100:101] op_sel_hi:[1,0]
	v_pk_mul_f32 v[88:89], v[88:89], v[100:101] op_sel_hi:[1,0]
	v_pk_mul_f32 v[86:87], v[86:87], v[100:101] op_sel_hi:[1,0]
	v_pk_mul_f32 v[84:85], v[84:85], v[100:101] op_sel_hi:[1,0]
	v_pk_mul_f32 v[102:103], v[82:83], v[100:101] op_sel_hi:[1,0]
	v_pk_mul_f32 v[100:101], v[80:81], v[100:101] op_sel_hi:[1,0]
	v_cvt_pk_bf16_f32 v80, v92, v93
	v_cvt_pk_bf16_f32 v81, v94, v95
	v_cvt_pk_bf16_f32 v82, v88, v89
	v_cvt_pk_bf16_f32 v83, v90, v91
	v_cvt_pk_bf16_f32 v84, v84, v85
	v_cvt_pk_bf16_f32 v85, v86, v87
	v_cvt_pk_bf16_f32 v86, v100, v101
	v_cvt_pk_bf16_f32 v87, v102, v103
	global_store_dwordx4 v[96:97], v[80:83], off
	global_store_dwordx4 v[96:97], v[84:87], off offset:256
	s_nop 1
	v_mov_b32_e32 v84, v247
	v_mad_i64_i32 v[80:81], s[34:35], v158, s73, v[120:121]
	v_lshl_add_u64 v[80:81], v[80:81], 0, v[122:123]
	v_lshl_add_u64 v[82:83], v[160:161], 2, s[62:63]
	v_mul_f32_e32 v84, 0x3dd53b94, v84
	v_pk_mul_f32 v[78:79], v[78:79], v[84:85] op_sel_hi:[1,0]
	v_pk_mul_f32 v[76:77], v[76:77], v[84:85] op_sel_hi:[1,0]
	v_pk_mul_f32 v[74:75], v[74:75], v[84:85] op_sel_hi:[1,0]
	v_pk_mul_f32 v[72:73], v[72:73], v[84:85] op_sel_hi:[1,0]
	v_pk_mul_f32 v[70:71], v[70:71], v[84:85] op_sel_hi:[1,0]
	v_pk_mul_f32 v[68:69], v[68:69], v[84:85] op_sel_hi:[1,0]
	v_pk_mul_f32 v[86:87], v[66:67], v[84:85] op_sel_hi:[1,0]
	v_pk_mul_f32 v[84:85], v[64:65], v[84:85] op_sel_hi:[1,0]
	v_cvt_pk_bf16_f32 v64, v76, v77
	v_cvt_pk_bf16_f32 v65, v78, v79
	v_cvt_pk_bf16_f32 v66, v72, v73
	v_cvt_pk_bf16_f32 v67, v74, v75
	v_cvt_pk_bf16_f32 v68, v68, v69
	v_cvt_pk_bf16_f32 v69, v70, v71
	v_cvt_pk_bf16_f32 v70, v84, v85
	v_cvt_pk_bf16_f32 v71, v86, v87
	global_store_dwordx4 v[80:81], v[64:67], off
	global_store_dwordx4 v[80:81], v[68:71], off offset:256
	s_nop 1
	v_mov_b32_e32 v68, v248
	v_lshlrev_b32_e32 v64, 1, v154
	v_mad_i64_i32 v[66:67], s[34:35], v156, s73, v[120:121]
	v_ashrrev_i32_e32 v65, 31, v64
	v_lshl_add_u64 v[66:67], v[66:67], 0, v[122:123]
	v_lshl_add_u64 v[64:65], v[64:65], 2, s[62:63]
	v_mul_f32_e32 v68, 0x3dd53b94, v68
	v_pk_mul_f32 v[62:63], v[62:63], v[68:69] op_sel_hi:[1,0]
	v_pk_mul_f32 v[60:61], v[60:61], v[68:69] op_sel_hi:[1,0]
	v_pk_mul_f32 v[58:59], v[58:59], v[68:69] op_sel_hi:[1,0]
	v_pk_mul_f32 v[56:57], v[56:57], v[68:69] op_sel_hi:[1,0]
	v_pk_mul_f32 v[54:55], v[54:55], v[68:69] op_sel_hi:[1,0]
	v_pk_mul_f32 v[52:53], v[52:53], v[68:69] op_sel_hi:[1,0]
	v_pk_mul_f32 v[70:71], v[50:51], v[68:69] op_sel_hi:[1,0]
	v_pk_mul_f32 v[68:69], v[48:49], v[68:69] op_sel_hi:[1,0]
	v_cvt_pk_bf16_f32 v48, v60, v61
	v_cvt_pk_bf16_f32 v49, v62, v63
	v_cvt_pk_bf16_f32 v50, v56, v57
	v_cvt_pk_bf16_f32 v51, v58, v59
	v_cvt_pk_bf16_f32 v52, v52, v53
	v_cvt_pk_bf16_f32 v53, v54, v55
	v_cvt_pk_bf16_f32 v54, v68, v69
	v_cvt_pk_bf16_f32 v55, v70, v71
	global_store_dwordx4 v[66:67], v[48:51], off
	global_store_dwordx4 v[66:67], v[52:55], off offset:256
	s_nop 1
	v_mov_b32_e32 v52, v249
	v_lshlrev_b32_e32 v48, 1, v152
	v_mad_i64_i32 v[50:51], s[34:35], v154, s73, v[120:121]
	v_ashrrev_i32_e32 v49, 31, v48
	v_lshl_add_u64 v[50:51], v[50:51], 0, v[122:123]
	v_lshl_add_u64 v[48:49], v[48:49], 2, s[62:63]
	v_mul_f32_e32 v52, 0x3dd53b94, v52
	v_pk_mul_f32 v[46:47], v[46:47], v[52:53] op_sel_hi:[1,0]
	v_pk_mul_f32 v[44:45], v[44:45], v[52:53] op_sel_hi:[1,0]
	v_pk_mul_f32 v[42:43], v[42:43], v[52:53] op_sel_hi:[1,0]
	v_pk_mul_f32 v[40:41], v[40:41], v[52:53] op_sel_hi:[1,0]
	v_pk_mul_f32 v[38:39], v[38:39], v[52:53] op_sel_hi:[1,0]
	v_pk_mul_f32 v[36:37], v[36:37], v[52:53] op_sel_hi:[1,0]
	v_pk_mul_f32 v[54:55], v[34:35], v[52:53] op_sel_hi:[1,0]
	v_pk_mul_f32 v[52:53], v[32:33], v[52:53] op_sel_hi:[1,0]
	v_cvt_pk_bf16_f32 v32, v44, v45
	v_cvt_pk_bf16_f32 v33, v46, v47
	v_cvt_pk_bf16_f32 v34, v40, v41
	v_cvt_pk_bf16_f32 v35, v42, v43
	v_cvt_pk_bf16_f32 v36, v36, v37
	v_cvt_pk_bf16_f32 v37, v38, v39
	v_cvt_pk_bf16_f32 v38, v52, v53
	v_cvt_pk_bf16_f32 v39, v54, v55
	global_store_dwordx4 v[50:51], v[32:35], off
	global_store_dwordx4 v[50:51], v[36:39], off offset:256
	s_nop 1
	v_mov_b32_e32 v36, v250
	v_lshlrev_b32_e32 v32, 1, v150
	v_mad_i64_i32 v[34:35], s[34:35], v152, s73, v[120:121]
	v_ashrrev_i32_e32 v33, 31, v32
	v_lshl_add_u64 v[34:35], v[34:35], 0, v[122:123]
	v_lshl_add_u64 v[32:33], v[32:33], 2, s[62:63]
	v_mul_f32_e32 v36, 0x3dd53b94, v36
	v_pk_mul_f32 v[30:31], v[30:31], v[36:37] op_sel_hi:[1,0]
	v_pk_mul_f32 v[28:29], v[28:29], v[36:37] op_sel_hi:[1,0]
	v_pk_mul_f32 v[26:27], v[26:27], v[36:37] op_sel_hi:[1,0]
	v_pk_mul_f32 v[24:25], v[24:25], v[36:37] op_sel_hi:[1,0]
	v_pk_mul_f32 v[22:23], v[22:23], v[36:37] op_sel_hi:[1,0]
	v_pk_mul_f32 v[20:21], v[20:21], v[36:37] op_sel_hi:[1,0]
	v_pk_mul_f32 v[38:39], v[18:19], v[36:37] op_sel_hi:[1,0]
	v_pk_mul_f32 v[36:37], v[16:17], v[36:37] op_sel_hi:[1,0]
	v_cvt_pk_bf16_f32 v16, v28, v29
	v_cvt_pk_bf16_f32 v17, v30, v31
	v_cvt_pk_bf16_f32 v18, v24, v25
	v_cvt_pk_bf16_f32 v19, v26, v27
	v_cvt_pk_bf16_f32 v20, v20, v21
	v_cvt_pk_bf16_f32 v21, v22, v23
	v_cvt_pk_bf16_f32 v22, v36, v37
	v_cvt_pk_bf16_f32 v23, v38, v39
	global_store_dwordx4 v[34:35], v[16:19], off
	global_store_dwordx4 v[34:35], v[20:23], off offset:256
	s_nop 1
	v_mov_b32_e32 v18, v251
	v_mad_i64_i32 v[16:17], s[34:35], v150, s73, v[120:121]
	v_lshl_add_u64 v[16:17], v[16:17], 0, v[122:123]
	v_mul_f32_e32 v18, 0x3dd53b94, v18
	v_pk_mul_f32 v[14:15], v[14:15], v[18:19] op_sel_hi:[1,0]
	v_pk_mul_f32 v[12:13], v[12:13], v[18:19] op_sel_hi:[1,0]
	v_pk_mul_f32 v[10:11], v[10:11], v[18:19] op_sel_hi:[1,0]
	v_pk_mul_f32 v[8:9], v[8:9], v[18:19] op_sel_hi:[1,0]
	v_pk_mul_f32 v[6:7], v[6:7], v[18:19] op_sel_hi:[1,0]
	v_pk_mul_f32 v[4:5], v[4:5], v[18:19] op_sel_hi:[1,0]
	v_pk_mul_f32 v[20:21], v[2:3], v[18:19] op_sel_hi:[1,0]
	v_pk_mul_f32 v[18:19], v[0:1], v[18:19] op_sel_hi:[1,0]
	v_cvt_pk_bf16_f32 v0, v12, v13
	v_cvt_pk_bf16_f32 v1, v14, v15
	v_cvt_pk_bf16_f32 v2, v8, v9
	v_cvt_pk_bf16_f32 v3, v10, v11
	v_cvt_pk_bf16_f32 v4, v4, v5
	v_cvt_pk_bf16_f32 v5, v6, v7
	v_cvt_pk_bf16_f32 v6, v18, v19
	v_cvt_pk_bf16_f32 v7, v20, v21
	global_store_dwordx4 v[16:17], v[0:3], off
	global_store_dwordx4 v[16:17], v[4:7], off offset:256
	s_and_b64 vcc, exec, s[6:7]
	s_mov_b64 s[6:7], -1
	s_cbranch_vccnz .LBB0_1399
